# P4: touch x tile rows at tile start (prefetch residual operand during main loop)
# baseline (speedup 1.0000x reference)
; template <class Epi, class Sched, bool ALIGN_EPI = false, bool SP2 = false>
; __device__ __forceinline__ void gemm_phase(PG8_LAS unsigned char* lds, const Gemm g, const Sched& S, const Epi& E, const int wv) {
;     ...
;         const bool has_next = S.next(ui + 1, nxt);
;         const char* nA = has_next ? (const char*)g.A + (size_t)nxt.pm * tstep : cA; const char* nB = has_next ? (const char*)g.Bt + (size_t)nxt.pn * tstep : cB;
;         for (int t = 0; t < nt; t += 2) {
;             if constexpr (Epi::HAS_MID) { if (t == (nt >> 1)) E.mid(acc, cur, wr, wc, fr, fq); }
;             const bool last = (t == nt - 2);
;             const char* a1 = cA + (size_t)(t + 1) * kstep;
;             const char* a2 = last ? nA : cA + (size_t)(t + 2) * kstep; const char* b2 = last ? nB : cB + (size_t)(t + 2) * kstep;
;     ...
; #pragma unroll
;         for (int a = 0; a < 2; ++a)
; #pragma unroll
;             for (int b = 0; b < 2; ++b)
; #pragma unroll
;                 for (int m = 0; m < 4; ++m)
; #pragma unroll
;                     for (int n = 0; n < 2; ++n) acc[a][b][m][n] = (f32x4){0.f, 0.f, 0.f, 0.f};
.LBB0_556:
	s_lshl_b32 s24, s46, 8
	s_add_i32 s24, s24, s66
	v_add_u32_e32 v0, s24, v212
	v_lshlrev_b32_e32 v0, 12, v0
	s_lshl_b32 s24, s28, 10
	s_lshl_b32 s25, s63, 7
	s_add_i32 s24, s24, s25
	v_add_u32_e32 v0, s24, v0
	global_load_dword v230, v0, s[26:27]
	global_load_dword v230, v0, s[26:27] offset:512
	v_add_u32_e32 v0, 0x80000, v0
	global_load_dword v230, v0, s[26:27]
	global_load_dword v230, v0, s[26:27] offset:512
	s_ashr_i32 s41, s40, 31
	s_lshl_b64 s[24:25], s[40:41], 19
	s_add_u32 s42, s77, s24
	s_addc_u32 s43, s78, s25
	s_and_b64 s[24:25], s[14:15], exec
	s_cselect_b32 s41, s43, s49
	s_cselect_b32 s47, s42, s48
	s_ashr_i32 s39, s38, 31
	s_lshl_b64 s[24:25], s[38:39], 19
	s_add_u32 s44, s75, s24
	s_addc_u32 s45, s76, s25
	s_and_b64 s[24:25], s[14:15], exec
	s_cselect_b32 s39, s45, s51
	s_cselect_b32 s55, s44, s50
	s_add_u32 s48, s48, 0x40080
	s_addc_u32 s49, s49, 0
	s_add_u32 s58, s50, 0x100
	v_mov_b32_e32 v0, 0
	s_addc_u32 s65, s51, 0
	s_mov_b32 s70, -2
	s_waitcnt lgkmcnt(0)
	v_mov_b32_e32 v1, v0
	v_mov_b32_e32 v2, v0
	v_mov_b32_e32 v3, v0
	v_mov_b32_e32 v4, v0
	v_mov_b32_e32 v5, v0
	v_mov_b32_e32 v6, v0
	v_mov_b32_e32 v7, v0
	v_mov_b32_e32 v16, v0
	v_mov_b32_e32 v17, v0
	v_mov_b32_e32 v18, v0
	v_mov_b32_e32 v19, v0
	v_mov_b32_e32 v20, v0
	v_mov_b32_e32 v21, v0
	v_mov_b32_e32 v22, v0
	v_mov_b32_e32 v23, v0
	v_mov_b32_e32 v32, v0
	v_mov_b32_e32 v33, v0
	v_mov_b32_e32 v34, v0
	v_mov_b32_e32 v35, v0
	v_mov_b32_e32 v36, v0
	v_mov_b32_e32 v37, v0
	v_mov_b32_e32 v38, v0
	v_mov_b32_e32 v39, v0
	v_mov_b32_e32 v48, v0
	v_mov_b32_e32 v49, v0
	v_mov_b32_e32 v50, v0
	v_mov_b32_e32 v51, v0
	v_mov_b32_e32 v52, v0
	v_mov_b32_e32 v53, v0
	v_mov_b32_e32 v54, v0
	v_mov_b32_e32 v55, v0
	v_mov_b32_e32 v8, v0
	v_mov_b32_e32 v9, v0
	v_mov_b32_e32 v10, v0
	v_mov_b32_e32 v11, v0
	v_mov_b32_e32 v12, v0
	v_mov_b32_e32 v13, v0
	v_mov_b32_e32 v14, v0
	v_mov_b32_e32 v15, v0
	v_mov_b32_e32 v24, v0
	v_mov_b32_e32 v25, v0
	v_mov_b32_e32 v26, v0
	v_mov_b32_e32 v27, v0
	v_mov_b32_e32 v28, v0
	v_mov_b32_e32 v29, v0
	v_mov_b32_e32 v30, v0
	v_mov_b32_e32 v31, v0
	v_mov_b32_e32 v40, v0
	v_mov_b32_e32 v41, v0
	v_mov_b32_e32 v42, v0
	v_mov_b32_e32 v43, v0
	v_mov_b32_e32 v44, v0
	v_mov_b32_e32 v45, v0
	v_mov_b32_e32 v46, v0
	v_mov_b32_e32 v47, v0
	v_mov_b32_e32 v56, v0
	v_mov_b32_e32 v57, v0
	v_mov_b32_e32 v58, v0
	v_mov_b32_e32 v59, v0
	v_mov_b32_e32 v60, v0
	v_mov_b32_e32 v61, v0
	v_mov_b32_e32 v62, v0
	v_mov_b32_e32 v63, v0
	v_mov_b32_e32 v64, v0
	v_mov_b32_e32 v65, v0
	v_mov_b32_e32 v66, v0
	v_mov_b32_e32 v67, v0
	v_mov_b32_e32 v68, v0
	v_mov_b32_e32 v69, v0
	v_mov_b32_e32 v70, v0
	v_mov_b32_e32 v71, v0
	v_mov_b32_e32 v80, v0
	v_mov_b32_e32 v81, v0
	v_mov_b32_e32 v82, v0
	v_mov_b32_e32 v83, v0
	v_mov_b32_e32 v84, v0
	v_mov_b32_e32 v85, v0
	v_mov_b32_e32 v86, v0
	v_mov_b32_e32 v87, v0
	v_mov_b32_e32 v96, v0
	v_mov_b32_e32 v97, v0
	v_mov_b32_e32 v98, v0
	v_mov_b32_e32 v99, v0
	v_mov_b32_e32 v100, v0
	v_mov_b32_e32 v101, v0
	v_mov_b32_e32 v102, v0
	v_mov_b32_e32 v103, v0
	v_mov_b32_e32 v112, v0
	v_mov_b32_e32 v113, v0
	v_mov_b32_e32 v114, v0
	v_mov_b32_e32 v115, v0
	v_mov_b32_e32 v116, v0
	v_mov_b32_e32 v117, v0
	v_mov_b32_e32 v118, v0
	v_mov_b32_e32 v119, v0
	v_mov_b32_e32 v72, v0
	v_mov_b32_e32 v73, v0
	v_mov_b32_e32 v74, v0
	v_mov_b32_e32 v75, v0
	v_mov_b32_e32 v76, v0
	v_mov_b32_e32 v77, v0
	v_mov_b32_e32 v78, v0
	v_mov_b32_e32 v79, v0
	v_mov_b32_e32 v88, v0
	v_mov_b32_e32 v89, v0
	v_mov_b32_e32 v90, v0
	v_mov_b32_e32 v91, v0
	v_mov_b32_e32 v92, v0
	v_mov_b32_e32 v93, v0
	v_mov_b32_e32 v94, v0
	v_mov_b32_e32 v95, v0
	v_mov_b32_e32 v104, v0
	v_mov_b32_e32 v105, v0
	v_mov_b32_e32 v106, v0
	v_mov_b32_e32 v107, v0
	v_mov_b32_e32 v108, v0
	v_mov_b32_e32 v109, v0
	v_mov_b32_e32 v110, v0
	v_mov_b32_e32 v111, v0
	v_mov_b32_e32 v120, v0
	v_mov_b32_e32 v121, v0
	v_mov_b32_e32 v122, v0
	v_mov_b32_e32 v123, v0
	v_mov_b32_e32 v124, v0
	v_mov_b32_e32 v125, v0
	v_mov_b32_e32 v126, v0
	v_mov_b32_e32 v127, v0
